# barrier: arrival-counter polling plus removal of the now-unused generation increments (no write acks on the leader path)
# speedup vs baseline: 1.0022x; 1.0011x over previous
.LBB0_147:
	s_or_b64 exec, exec, s[28:29]
	v_cvt_f32_u32_e32 v4, v2
	s_waitcnt vmcnt(0)
	v_readfirstlane_b32 s0, v3
	v_readlane_b32 s14, v251, 52
	v_readlane_b32 s15, v251, 53
	v_rcp_iflag_f32_e32 v4, v4
	v_add_u32_e32 v0, s0, v0
	v_add_u32_e32 v5, 1, v0
	s_mov_b64 s[28:29], 0
	v_mul_f32_e32 v3, 0x4f7ffffe, v4
	v_cvt_u32_f32_e32 v3, v3
	v_sub_u32_e32 v4, 0, v2
	v_mul_lo_u32 v4, v4, v3
	v_mul_hi_u32 v4, v3, v4
	v_add_u32_e32 v3, v3, v4
	v_mul_hi_u32 v3, v0, v3
	v_mul_lo_u32 v4, v3, v2
	v_sub_u32_e32 v0, v0, v4
	v_add_u32_e32 v6, 1, v3
	v_cmp_ge_u32_e32 vcc, v0, v2
	v_sub_u32_e32 v4, v0, v2
	s_nop 0
	v_cndmask_b32_e32 v3, v3, v6, vcc
	v_cndmask_b32_e32 v0, v0, v4, vcc
	v_add_u32_e32 v4, 1, v3
	v_cmp_ge_u32_e32 vcc, v0, v2
	s_nop 1
	v_cndmask_b32_e32 v0, v3, v4, vcc
	v_mul_lo_u32 v3, v2, v0
	v_add_u32_e32 v2, v3, v2
	v_mov_b32_e32 v0, v2
	v_cmp_ne_u32_e32 vcc, v5, v2
	v_mov_b64_e32 v[2:3], s[14:15]
	s_and_saveexec_b64 s[26:27], vcc
	s_cbranch_execz .LBB0_159
	v_readlane_b32 s14, v251, 50
	v_readlane_b32 s15, v251, 51
	s_mov_b64 s[30:31], 0
	s_nop 3
	global_load_dword v2, v1, s[14:15] sc1
	s_waitcnt vmcnt(0)
	v_cmp_lt_u32_e32 vcc, v2, v0
	s_and_saveexec_b64 s[28:29], vcc
	s_cbranch_execz .LBB0_158
	s_mov_b32 s0, 1
	s_branch .LBB0_151

.LBB0_275:
	s_or_b64 exec, exec, s[28:29]
	s_waitcnt vmcnt(0)
	v_readfirstlane_b32 s0, v3
	v_sub_u32_e32 v4, 0, v2
	v_readlane_b32 s14, v251, 52
	v_add_u32_e32 v3, s0, v0
	v_cvt_f32_u32_e32 v0, v2
	v_readlane_b32 s15, v251, 53
	s_mov_b64 s[28:29], 0
	v_rcp_iflag_f32_e32 v0, v0
	s_nop 0
	v_mul_f32_e32 v0, 0x4f7ffffe, v0
	v_cvt_u32_f32_e32 v0, v0
	v_mul_lo_u32 v4, v4, v0
	v_mul_hi_u32 v4, v0, v4
	v_add_u32_e32 v0, v0, v4
	v_mul_hi_u32 v0, v3, v0
	v_mul_lo_u32 v4, v0, v2
	v_sub_u32_e32 v4, v3, v4
	v_cmp_ge_u32_e32 vcc, v4, v2
	v_add_u32_e32 v5, 1, v0
	v_add_u32_e32 v3, 1, v3
	v_cndmask_b32_e32 v0, v0, v5, vcc
	v_sub_u32_e32 v5, v4, v2
	v_cndmask_b32_e32 v4, v4, v5, vcc
	v_cmp_ge_u32_e32 vcc, v4, v2
	v_add_u32_e32 v4, 1, v0
	s_nop 0
	v_cndmask_b32_e32 v0, v0, v4, vcc
	v_mul_lo_u32 v4, v2, v0
	v_add_u32_e32 v2, v4, v2
	v_mov_b32_e32 v0, v2
	v_cmp_ne_u32_e32 vcc, v3, v2
	v_mov_b64_e32 v[2:3], s[14:15]
	s_and_saveexec_b64 s[26:27], vcc
	s_cbranch_execz .LBB0_287
	v_readlane_b32 s14, v251, 50
	v_readlane_b32 s15, v251, 51
	s_mov_b64 s[30:31], 0
	s_nop 3
	global_load_dword v2, v1, s[14:15] sc1
	s_waitcnt vmcnt(0)
	v_cmp_lt_u32_e32 vcc, v2, v0
	s_and_saveexec_b64 s[28:29], vcc
	s_cbranch_execz .LBB0_286
	s_mov_b32 s0, 1
	s_branch .LBB0_279
